# v16 + P0 tile-top vmcnt(4) kept as load/store ordering guard
# speedup vs baseline: 1.0076x; 1.0076x over previous
; #define GAS __attribute__((address_space(1)))
; template <class Epi, class Sched, bool ALIGN_EPI, bool SP2>
; __device__ __forceinline__ void gemm_phase(LAS unsigned char* lds, const int tid, const Gemm g, const Sched& S, const Epi& E) {
;     ...
;         if (rst) {
; #pragma unroll
;         for (int a = 0; a < 2; ++a)
; #pragma unroll
;             for (int b = 0; b < 2; ++b)
; #pragma unroll
;                 for (int m = 0; m < 4; ++m)
; #pragma unroll
;                     for (int n = 0; n < 2; ++n) acc[a][b][m][n] = (f32x4){0.f, 0.f, 0.f, 0.f};
;         }
;         cur = nxt; cA = nA; cB = nB; ++ui;
;     __device__ __forceinline__ void operator()(const f32x4 (&acc)[2][2][4][2], const Unit& u, int wr, int wc, int fr, int fq) const {
;         const int row0 = u.pm * BM + wr * 64 + fr, col0 = u.pn * BM + wc * 32 + 8 * fq;
;         f32x4 bv[2][2];
; #pragma unroll
;         for (int bj = 0; bj < 2; ++bj)
; #pragma unroll
;             for (int n = 0; n < 2; ++n) bv[bj][n] = bias ? *(const GAS f32x4*)(bias + col0 + bj * HALF + 4 * n) : (f32x4){0.f, 0.f, 0.f, 0.f};
.LBB0_462:
	v_mov_b64_e32 v[2:3], 0x6c0
	s_ashr_i32 s23, s22, 31
	v_cmp_lt_i64_e32 vcc, s[24:25], v[2:3]
	s_lshl_b64 s[24:25], s[22:23], 20
	s_add_u32 s24, s5, s24
	s_addc_u32 s25, s44, s25
	s_and_b64 s[26:27], vcc, exec
	s_cselect_b32 s23, s25, s41
	s_cselect_b32 s58, s24, s40
	s_ashr_i32 s19, s18, 31
	s_lshl_b64 s[26:27], s[18:19], 20
	s_add_u32 s26, s45, s26
	s_addc_u32 s27, s46, s27
	s_and_b64 s[42:43], vcc, exec
	s_cselect_b32 s19, s27, s35
	s_cselect_b32 s59, s26, s34
	s_add_u32 s60, s34, 0x100
	s_addc_u32 s61, s35, 0
	s_add_u32 s34, s40, 0x80080
	v_lshl_or_b32 v158, s56, 8, v161
	v_ashrrev_i32_e32 v159, 31, v158
	v_lshl_add_u64 v[156:157], v[158:159], 2, s[10:11]
	global_load_dwordx4 v[228:231], v[156:157], off
	global_load_dwordx4 v[232:235], v[156:157], off offset:16
	global_load_dwordx4 v[236:239], v[156:157], off offset:512
	global_load_dwordx4 v[240:243], v[156:157], off offset:528
	v_mov_b32_e32 v2, 0
	s_addc_u32 s35, s41, 0
	s_mov_b32 s62, -2
	v_mov_b32_e32 v3, v2
	v_mov_b32_e32 v4, v2
	v_mov_b32_e32 v5, v2
	v_mov_b32_e32 v6, v2
	v_mov_b32_e32 v7, v2
	v_mov_b32_e32 v8, v2
	v_mov_b32_e32 v9, v2
	v_mov_b32_e32 v14, v2
	v_mov_b32_e32 v15, v2
	v_mov_b32_e32 v16, v2
	v_mov_b32_e32 v17, v2
	s_waitcnt vmcnt(4)
	v_mov_b32_e32 v22, v2
	v_mov_b32_e32 v23, v2
	v_mov_b32_e32 v24, v2
	v_mov_b32_e32 v25, v2
	v_mov_b32_e32 v30, v2
	v_mov_b32_e32 v31, v2
	v_mov_b32_e32 v32, v2
	v_mov_b32_e32 v33, v2
	v_mov_b32_e32 v38, v2
	v_mov_b32_e32 v39, v2
	v_mov_b32_e32 v40, v2
	v_mov_b32_e32 v41, v2
	v_mov_b32_e32 v46, v2
	v_mov_b32_e32 v47, v2
	v_mov_b32_e32 v48, v2
	v_mov_b32_e32 v49, v2
	v_mov_b32_e32 v54, v2
	v_mov_b32_e32 v55, v2
	v_mov_b32_e32 v56, v2
	v_mov_b32_e32 v57, v2
	v_mov_b32_e32 v10, v2
	v_mov_b32_e32 v11, v2
	v_mov_b32_e32 v12, v2
	v_mov_b32_e32 v13, v2
	v_mov_b32_e32 v18, v2
	v_mov_b32_e32 v19, v2
	v_mov_b32_e32 v20, v2
	v_mov_b32_e32 v21, v2
	v_mov_b32_e32 v26, v2
	v_mov_b32_e32 v27, v2
	v_mov_b32_e32 v28, v2
	v_mov_b32_e32 v29, v2
	v_mov_b32_e32 v34, v2
	v_mov_b32_e32 v35, v2
	v_mov_b32_e32 v36, v2
	v_mov_b32_e32 v37, v2
	v_mov_b32_e32 v42, v2
	v_mov_b32_e32 v43, v2
	v_mov_b32_e32 v44, v2
	v_mov_b32_e32 v45, v2
	v_mov_b32_e32 v50, v2
	v_mov_b32_e32 v51, v2
	v_mov_b32_e32 v52, v2
	v_mov_b32_e32 v53, v2
	v_mov_b32_e32 v58, v2
	v_mov_b32_e32 v59, v2
	v_mov_b32_e32 v60, v2
	v_mov_b32_e32 v61, v2
	v_mov_b32_e32 v62, v2
	v_mov_b32_e32 v63, v2
	v_mov_b32_e32 v64, v2
	v_mov_b32_e32 v65, v2
	v_mov_b32_e32 v66, v2
	v_mov_b32_e32 v67, v2
	v_mov_b32_e32 v68, v2
	v_mov_b32_e32 v69, v2
	v_mov_b32_e32 v70, v2
	v_mov_b32_e32 v71, v2
	v_mov_b32_e32 v72, v2
	v_mov_b32_e32 v73, v2
	v_mov_b32_e32 v78, v2
	v_mov_b32_e32 v79, v2
	v_mov_b32_e32 v80, v2
	v_mov_b32_e32 v81, v2
	v_mov_b32_e32 v86, v2
	v_mov_b32_e32 v87, v2
	v_mov_b32_e32 v88, v2
	v_mov_b32_e32 v89, v2
	v_mov_b32_e32 v94, v2
	v_mov_b32_e32 v95, v2
	v_mov_b32_e32 v96, v2
	v_mov_b32_e32 v97, v2
	v_mov_b32_e32 v102, v2
	v_mov_b32_e32 v103, v2
	v_mov_b32_e32 v104, v2
	v_mov_b32_e32 v105, v2
	v_mov_b32_e32 v110, v2
	v_mov_b32_e32 v111, v2
	v_mov_b32_e32 v112, v2
	v_mov_b32_e32 v113, v2
	v_mov_b32_e32 v118, v2
	v_mov_b32_e32 v119, v2
	v_mov_b32_e32 v120, v2
	v_mov_b32_e32 v121, v2
	v_mov_b32_e32 v74, v2
	v_mov_b32_e32 v75, v2
	v_mov_b32_e32 v76, v2
	v_mov_b32_e32 v77, v2
	v_mov_b32_e32 v82, v2
	v_mov_b32_e32 v83, v2
	v_mov_b32_e32 v84, v2
	v_mov_b32_e32 v85, v2
	v_mov_b32_e32 v90, v2
	v_mov_b32_e32 v91, v2
	v_mov_b32_e32 v92, v2
	v_mov_b32_e32 v93, v2
	v_mov_b32_e32 v98, v2
	v_mov_b32_e32 v99, v2
	v_mov_b32_e32 v100, v2
	v_mov_b32_e32 v101, v2
	v_mov_b32_e32 v106, v2
	v_mov_b32_e32 v107, v2
	v_mov_b32_e32 v108, v2
	v_mov_b32_e32 v109, v2
	v_mov_b32_e32 v114, v2
	v_mov_b32_e32 v115, v2
	v_mov_b32_e32 v116, v2
	v_mov_b32_e32 v117, v2
	v_mov_b32_e32 v122, v2
	v_mov_b32_e32 v123, v2
	v_mov_b32_e32 v124, v2
	v_mov_b32_e32 v125, v2
	v_mov_b32_e32 v126, v2
	v_mov_b32_e32 v127, v2
	v_mov_b32_e32 v128, v2
	v_mov_b32_e32 v129, v2
